# grid barrier: non-leader workgroups poll the top generation word directly (one poll stage less)
# speedup vs baseline: 1.0047x; 1.0047x over previous
.LBB0_147:
	s_or_b64 exec, exec, s[12:13]
	v_cvt_f32_u32_e32 v6, v4
	s_waitcnt vmcnt(0)
	v_readfirstlane_b32 s0, v5
	v_sub_u32_e32 v5, 0, v4
	v_rcp_iflag_f32_e32 v6, v6
	v_add_u32_e32 v7, s0, v3
	v_mul_f32_e32 v6, 0x4f7ffffe, v6
	v_cvt_u32_f32_e32 v6, v6
	v_mul_lo_u32 v3, v5, v6
	v_mul_hi_u32 v3, v6, v3
	v_add_u32_e32 v3, v6, v3
	v_mul_hi_u32 v3, v7, v3
	v_mul_lo_u32 v5, v3, v4
	v_sub_u32_e32 v5, v7, v5
	v_add_u32_e32 v6, 1, v3
	v_cmp_ge_u32_e32 vcc, v5, v4
	s_nop 1
	v_cndmask_b32_e32 v3, v3, v6, vcc
	v_sub_u32_e32 v6, v5, v4
	v_cndmask_b32_e32 v5, v5, v6, vcc
	v_add_u32_e32 v6, 1, v3
	v_cmp_ge_u32_e32 vcc, v5, v4
	v_add_u32_e32 v5, 1, v7
	s_nop 0
	v_cndmask_b32_e32 v3, v3, v6, vcc
	v_mul_lo_u32 v6, v4, v3
	v_add_u32_e32 v4, v6, v4
	v_cmp_ne_u32_e32 vcc, v5, v4
	s_and_saveexec_b64 s[0:1], vcc
	s_xor_b64 s[10:11], exec, s[0:1]
	s_cbranch_execz .LBB0_161
	s_waitcnt lgkmcnt(0)
	v_mov_b32_e32 v2, 0x2b5c100
	global_load_dword v2, v2, s[88:89] offset:1024 sc1
	s_add_u32 s16, s88, 0x2b5c500
	s_addc_u32 s17, s89, 0
	s_waitcnt vmcnt(0)
	v_cmp_eq_u32_e32 vcc, v2, v3
	s_and_saveexec_b64 s[12:13], vcc
	s_cbranch_execz .LBB0_160
	s_add_u32 s14, s88, 0x2b59200
	s_addc_u32 s15, s89, 0
	s_mov_b32 s0, 1
	s_mov_b64 s[18:19], 0
	v_mov_b32_e32 v2, 0
	s_branch .LBB0_151

.LBB0_223:
	s_or_b64 exec, exec, s[14:15]
	v_cvt_f32_u32_e32 v6, v4
	s_waitcnt vmcnt(0)
	v_readfirstlane_b32 s0, v5
	v_sub_u32_e32 v5, 0, v4
	v_rcp_iflag_f32_e32 v6, v6
	v_add_u32_e32 v7, s0, v3
	v_mul_f32_e32 v6, 0x4f7ffffe, v6
	v_cvt_u32_f32_e32 v6, v6
	v_mul_lo_u32 v3, v5, v6
	v_mul_hi_u32 v3, v6, v3
	v_add_u32_e32 v3, v6, v3
	v_mul_hi_u32 v3, v7, v3
	v_mul_lo_u32 v5, v3, v4
	v_sub_u32_e32 v5, v7, v5
	v_add_u32_e32 v6, 1, v3
	v_cmp_ge_u32_e32 vcc, v5, v4
	s_nop 1
	v_cndmask_b32_e32 v3, v3, v6, vcc
	v_sub_u32_e32 v6, v5, v4
	v_cndmask_b32_e32 v5, v5, v6, vcc
	v_add_u32_e32 v6, 1, v3
	v_cmp_ge_u32_e32 vcc, v5, v4
	v_add_u32_e32 v5, 1, v7
	s_nop 0
	v_cndmask_b32_e32 v3, v3, v6, vcc
	v_mul_lo_u32 v6, v4, v3
	v_add_u32_e32 v4, v6, v4
	v_cmp_ne_u32_e32 vcc, v5, v4
	s_and_saveexec_b64 s[0:1], vcc
	s_xor_b64 s[12:13], exec, s[0:1]
	s_cbranch_execz .LBB0_237
	s_waitcnt lgkmcnt(0)
	v_mov_b32_e32 v2, 0x2b5c100
	global_load_dword v2, v2, s[88:89] offset:1024 sc1
	s_add_u32 s18, s88, 0x2b5c500
	s_addc_u32 s19, s89, 0
	s_waitcnt vmcnt(0)
	v_cmp_eq_u32_e32 vcc, v2, v3
	s_and_saveexec_b64 s[14:15], vcc
	s_cbranch_execz .LBB0_236
	s_add_u32 s16, s88, 0x2b59200
	s_addc_u32 s17, s89, 0
	s_mov_b32 s0, 1
	s_mov_b64 s[20:21], 0
	v_mov_b32_e32 v2, 0
	s_branch .LBB0_227

.LBB0_343:
	s_or_b64 exec, exec, s[16:17]
	v_cvt_f32_u32_e32 v6, v4
	s_waitcnt vmcnt(0)
	v_readfirstlane_b32 s0, v5
	v_sub_u32_e32 v5, 0, v4
	v_rcp_iflag_f32_e32 v6, v6
	v_add_u32_e32 v7, s0, v3
	v_mul_f32_e32 v6, 0x4f7ffffe, v6
	v_cvt_u32_f32_e32 v6, v6
	v_mul_lo_u32 v3, v5, v6
	v_mul_hi_u32 v3, v6, v3
	v_add_u32_e32 v3, v6, v3
	v_mul_hi_u32 v3, v7, v3
	v_mul_lo_u32 v5, v3, v4
	v_sub_u32_e32 v5, v7, v5
	v_add_u32_e32 v6, 1, v3
	v_cmp_ge_u32_e32 vcc, v5, v4
	s_nop 1
	v_cndmask_b32_e32 v3, v3, v6, vcc
	v_sub_u32_e32 v6, v5, v4
	v_cndmask_b32_e32 v5, v5, v6, vcc
	v_add_u32_e32 v6, 1, v3
	v_cmp_ge_u32_e32 vcc, v5, v4
	v_add_u32_e32 v5, 1, v7
	s_nop 0
	v_cndmask_b32_e32 v3, v3, v6, vcc
	v_mul_lo_u32 v6, v4, v3
	v_add_u32_e32 v4, v6, v4
	v_cmp_ne_u32_e32 vcc, v5, v4
	s_and_saveexec_b64 s[0:1], vcc
	s_xor_b64 s[14:15], exec, s[0:1]
	s_cbranch_execz .LBB0_357
	s_waitcnt lgkmcnt(0)
	v_mov_b32_e32 v2, 0x2b5c100
	global_load_dword v2, v2, s[88:89] offset:1024 sc1
	s_add_u32 s20, s88, 0x2b5c500
	s_addc_u32 s21, s89, 0
	s_waitcnt vmcnt(0)
	v_cmp_eq_u32_e32 vcc, v2, v3
	s_and_saveexec_b64 s[16:17], vcc
	s_cbranch_execz .LBB0_356
	s_add_u32 s18, s88, 0x2b59200
	s_addc_u32 s19, s89, 0
	s_mov_b32 s0, 1
	s_mov_b64 s[22:23], 0
	v_mov_b32_e32 v2, 0
	s_branch .LBB0_347

.LBB0_1082:
	s_or_b64 exec, exec, s[18:19]
	v_cvt_f32_u32_e32 v6, v4
	s_waitcnt vmcnt(0)
	v_readfirstlane_b32 s0, v5
	v_sub_u32_e32 v5, 0, v4
	v_rcp_iflag_f32_e32 v6, v6
	v_add_u32_e32 v7, s0, v3
	v_mul_f32_e32 v6, 0x4f7ffffe, v6
	v_cvt_u32_f32_e32 v6, v6
	v_mul_lo_u32 v3, v5, v6
	v_mul_hi_u32 v3, v6, v3
	v_add_u32_e32 v3, v6, v3
	v_mul_hi_u32 v3, v7, v3
	v_mul_lo_u32 v5, v3, v4
	v_sub_u32_e32 v5, v7, v5
	v_add_u32_e32 v6, 1, v3
	v_cmp_ge_u32_e32 vcc, v5, v4
	s_nop 1
	v_cndmask_b32_e32 v3, v3, v6, vcc
	v_sub_u32_e32 v6, v5, v4
	v_cndmask_b32_e32 v5, v5, v6, vcc
	v_add_u32_e32 v6, 1, v3
	v_cmp_ge_u32_e32 vcc, v5, v4
	v_add_u32_e32 v5, 1, v7
	s_nop 0
	v_cndmask_b32_e32 v3, v3, v6, vcc
	v_mul_lo_u32 v6, v4, v3
	v_add_u32_e32 v4, v6, v4
	v_cmp_ne_u32_e32 vcc, v5, v4
	s_and_saveexec_b64 s[0:1], vcc
	s_xor_b64 s[14:15], exec, s[0:1]
	s_cbranch_execz .LBB0_1096
	s_waitcnt lgkmcnt(0)
	v_mov_b32_e32 v2, 0x2b5c100
	global_load_dword v2, v2, s[88:89] offset:1024 sc1
	s_add_u32 s22, s88, 0x2b5c500
	s_addc_u32 s23, s89, 0
	s_waitcnt vmcnt(0)
	v_cmp_eq_u32_e32 vcc, v2, v3
	s_and_saveexec_b64 s[18:19], vcc
	s_cbranch_execz .LBB0_1095
	s_add_u32 s20, s88, 0x2b59200
	s_addc_u32 s21, s89, 0
	s_mov_b32 s0, 1
	s_mov_b64 s[40:41], 0
	v_mov_b32_e32 v2, 0
	s_branch .LBB0_1086

.LBB0_1191:
	s_or_b64 exec, exec, s[18:19]
	v_cvt_f32_u32_e32 v6, v4
	s_waitcnt vmcnt(0)
	v_readfirstlane_b32 s0, v5
	v_sub_u32_e32 v5, 0, v4
	v_rcp_iflag_f32_e32 v6, v6
	v_add_u32_e32 v7, s0, v3
	v_mul_f32_e32 v6, 0x4f7ffffe, v6
	v_cvt_u32_f32_e32 v6, v6
	v_mul_lo_u32 v3, v5, v6
	v_mul_hi_u32 v3, v6, v3
	v_add_u32_e32 v3, v6, v3
	v_mul_hi_u32 v3, v7, v3
	v_mul_lo_u32 v5, v3, v4
	v_sub_u32_e32 v5, v7, v5
	v_add_u32_e32 v6, 1, v3
	v_cmp_ge_u32_e32 vcc, v5, v4
	s_nop 1
	v_cndmask_b32_e32 v3, v3, v6, vcc
	v_sub_u32_e32 v6, v5, v4
	v_cndmask_b32_e32 v5, v5, v6, vcc
	v_add_u32_e32 v6, 1, v3
	v_cmp_ge_u32_e32 vcc, v5, v4
	v_add_u32_e32 v5, 1, v7
	s_nop 0
	v_cndmask_b32_e32 v3, v3, v6, vcc
	v_mul_lo_u32 v6, v4, v3
	v_add_u32_e32 v4, v6, v4
	v_cmp_ne_u32_e32 vcc, v5, v4
	s_and_saveexec_b64 s[0:1], vcc
	s_xor_b64 s[14:15], exec, s[0:1]
	s_cbranch_execz .LBB0_1205
	s_waitcnt lgkmcnt(0)
	v_mov_b32_e32 v2, 0x2b5c100
	global_load_dword v2, v2, s[88:89] offset:1024 sc1
	s_add_u32 s22, s88, 0x2b5c500
	s_addc_u32 s23, s89, 0
	s_waitcnt vmcnt(0)
	v_cmp_eq_u32_e32 vcc, v2, v3
	s_and_saveexec_b64 s[18:19], vcc
	s_cbranch_execz .LBB0_1204
	s_add_u32 s20, s88, 0x2b59200
	s_addc_u32 s21, s89, 0
	s_mov_b32 s0, 1
	s_mov_b64 s[38:39], 0
	v_mov_b32_e32 v2, 0
	s_branch .LBB0_1195
